# indexer score loop: the two independent 4-MFMA accumulate chains interleaved
# speedup vs baseline: 1.0011x; 1.0011x over previous
; __device__ __forceinline__ void indexer_phase(const bf16_t* PJ, float* rk, unsigned short* SEL, LAS unsigned char* lds) {
;     ...
;                 const int kn = kt + NWAVE;
;                 if (kn < nkt) {
; #pragma unroll
;                     for (int kk = 0; kk < 4; ++kk) bnxt[kk] = *(const bf16x8*)(kbase + (size_t)(32 * kn) * PROJ_LD + kk * 16);
;                 }
;                 const int key = 32 * kt + r32;
; #pragma unroll
;                 for (int rt = 0; rt < 2; ++rt) {
;                     f32x16 acc = f32x16{};
; #pragma unroll
;                     for (int kk = 0; kk < 4; ++kk) acc = __builtin_amdgcn_mfma_f32_32x32x16_bf16(af[rt][kk], bcur[kk], acc, 0, 0, 0);
.Lidx_nofarA:
	s_waitcnt lgkmcnt(0)
	v_mfma_f32_32x32x16_bf16 v[0:15], v[72:75], v[244:247], 0
	v_mfma_f32_32x32x16_bf16 v[16:31], v[88:91], v[244:247], 0
	v_mfma_f32_32x32x16_bf16 v[0:15], v[64:67], v[104:107], v[0:15]
	v_mfma_f32_32x32x16_bf16 v[16:31], v[80:83], v[104:107], v[16:31]
	v_mfma_f32_32x32x16_bf16 v[0:15], v[68:71], v[100:103], v[0:15]
	v_mfma_f32_32x32x16_bf16 v[16:31], v[84:87], v[100:103], v[16:31]
	v_mfma_f32_32x32x16_bf16 v[0:15], v[76:79], v[96:99], v[0:15]
	v_mfma_f32_32x32x16_bf16 v[16:31], v[92:95], v[96:99], v[16:31]
	s_add_i32 s32, s1, 8
	s_cmp_lt_i32 s32, s0
	s_cbranch_scc1 .Lidx_w4A
	s_waitcnt vmcnt(0)
	s_branch .Lidx_trA

; #define LAS __attribute__((address_space(3)))
; __device__ __forceinline__ void indexer_phase(const bf16_t* PJ, float* rk, unsigned short* SEL, LAS unsigned char* lds) {
;     ...
;                     for (int qq = 0; qq < 2; ++qq) { float s = 0.f;
; #pragma unroll
;                         for (int e = 0; e < 8; ++e) s += wq[rt][qq][e] * fmaxf(acc[8 * qq + e], 0.f);
;                         ((LAS float*)lds)[(4 * rt + 2 * hi + qq) * 4096 + key] = s;
;                         const bool ok = key <= t0 + 4 * rt + 2 * hi + qq;
;                         rmax[rt][qq] = fmaxf(rmax[rt][qq], ok ? s : -INFINITY); rmin[rt][qq] = fminf(rmin[rt][qq], ok ? s : INFINITY); }
.Lidx_trA:
	ds_write_b128 v222, v[52:55]
	ds_write_b128 v222, v[56:59] offset:1024
	s_nop 7
	v_max_f32_e32 v0, 0, v0
	v_max_f32_e32 v1, 0, v1
	v_max_f32_e32 v2, 0, v2
	v_max_f32_e32 v3, 0, v3
	v_max_f32_e32 v4, 0, v4
	v_max_f32_e32 v5, 0, v5
	v_max_f32_e32 v6, 0, v6
	v_max_f32_e32 v7, 0, v7
	v_pk_mul_f32 v[0:1], v[126:127], v[0:1] op_sel:[1,0] op_sel_hi:[0,1]
	v_pk_fma_f32 v[0:1], v[128:129], v[2:3], v[0:1] op_sel:[1,0,0] op_sel_hi:[0,1,1]
	v_pk_fma_f32 v[0:1], v[130:131], v[4:5], v[0:1] op_sel:[1,0,0] op_sel_hi:[0,1,1]
	v_pk_fma_f32 v[0:1], v[132:133], v[6:7], v[0:1] op_sel:[1,0,0] op_sel_hi:[0,1,1]
	v_add_f32_e32 v0, v1, v0
	v_max_f32_e32 v8, 0, v8
	v_max_f32_e32 v9, 0, v9
	v_max_f32_e32 v10, 0, v10
	v_max_f32_e32 v11, 0, v11
	v_max_f32_e32 v12, 0, v12
	v_max_f32_e32 v13, 0, v13
	v_max_f32_e32 v14, 0, v14
	v_max_f32_e32 v15, 0, v15
	s_waitcnt lgkmcnt(0)
	ds_read_b128 v[244:247], v223
	ds_read_b128 v[104:107], v224
	v_pk_mul_f32 v[8:9], v[134:135], v[8:9] op_sel:[1,0] op_sel_hi:[0,1]
	v_pk_fma_f32 v[8:9], v[136:137], v[10:11], v[8:9] op_sel:[1,0,0] op_sel_hi:[0,1,1]
	v_pk_fma_f32 v[8:9], v[138:139], v[12:13], v[8:9] op_sel:[1,0,0] op_sel_hi:[0,1,1]
	v_pk_fma_f32 v[8:9], v[140:141], v[14:15], v[8:9] op_sel:[1,0,0] op_sel_hi:[0,1,1]
	v_add_f32_e32 v8, v9, v8
	v_max_f32_e32 v189, v189, v0
	v_min_f32_e32 v188, v188, v0
	ds_write2st64_b32 v196, v0, v8 offset1:64
	v_max_f32_e32 v16, 0, v16
	v_max_f32_e32 v17, 0, v17
	v_max_f32_e32 v18, 0, v18
	v_max_f32_e32 v19, 0, v19
	v_max_f32_e32 v20, 0, v20
	v_max_f32_e32 v21, 0, v21
	v_max_f32_e32 v22, 0, v22
	v_max_f32_e32 v23, 0, v23
	v_max_f32_e32 v187, v187, v8
	v_min_f32_e32 v186, v186, v8
	s_waitcnt lgkmcnt(0)
	ds_write_b128 v222, v[60:63]
	ds_write_b128 v222, v[48:51] offset:1024
	v_pk_mul_f32 v[16:17], v[142:143], v[16:17] op_sel:[1,0] op_sel_hi:[0,1]
	v_pk_fma_f32 v[16:17], v[144:145], v[18:19], v[16:17] op_sel:[1,0,0] op_sel_hi:[0,1,1]
	v_pk_fma_f32 v[16:17], v[146:147], v[20:21], v[16:17] op_sel:[1,0,0] op_sel_hi:[0,1,1]
	v_pk_fma_f32 v[16:17], v[148:149], v[22:23], v[16:17] op_sel:[1,0,0] op_sel_hi:[0,1,1]
	v_add_f32_e32 v16, v17, v16
	v_max_f32_e32 v24, 0, v24
	v_max_f32_e32 v25, 0, v25
	v_max_f32_e32 v26, 0, v26
	v_max_f32_e32 v27, 0, v27
	v_max_f32_e32 v28, 0, v28
	v_max_f32_e32 v29, 0, v29
	v_max_f32_e32 v30, 0, v30
	v_max_f32_e32 v31, 0, v31
	v_add_u32_e32 v3, 0x10000, v196
	s_waitcnt lgkmcnt(0)
	ds_read_b128 v[100:103], v223
	ds_read_b128 v[96:99], v224
	v_pk_mul_f32 v[24:25], v[150:151], v[24:25] op_sel:[1,0] op_sel_hi:[0,1]
	v_pk_fma_f32 v[24:25], v[152:153], v[26:27], v[24:25] op_sel:[1,0,0] op_sel_hi:[0,1,1]
	v_pk_fma_f32 v[24:25], v[154:155], v[28:29], v[24:25] op_sel:[1,0,0] op_sel_hi:[0,1,1]
	v_pk_fma_f32 v[24:25], v[156:157], v[30:31], v[24:25] op_sel:[1,0,0] op_sel_hi:[0,1,1]
	v_add_f32_e32 v24, v25, v24
	ds_write_b32 v3, v16
	v_max_f32_e32 v185, v185, v16
	v_min_f32_e32 v184, v184, v16
	v_add_u32_e32 v3, 0x14000, v196
	v_add_u32_e32 v196, 0x400, v196
	s_nop 0
	ds_write_b32 v3, v24
	v_max_f32_e32 v183, v183, v24
	v_min_f32_e32 v123, v123, v24
	s_mov_b32 s6, s3

; #define LAS __attribute__((address_space(3)))
; __device__ __forceinline__ void indexer_phase(const bf16_t* PJ, float* rk, unsigned short* SEL, LAS unsigned char* lds) {
;     ...
;                 const int key = 32 * kt + r32;
; #pragma unroll
;                 for (int rt = 0; rt < 2; ++rt) {
;                     f32x16 acc = f32x16{};
; #pragma unroll
;                     for (int kk = 0; kk < 4; ++kk) acc = __builtin_amdgcn_mfma_f32_32x32x16_bf16(af[rt][kk], bcur[kk], acc, 0, 0, 0);
; #pragma unroll
;                     for (int qq = 0; qq < 2; ++qq) { float s = 0.f;
; #pragma unroll
;                         for (int e = 0; e < 8; ++e) s += wq[rt][qq][e] * fmaxf(acc[8 * qq + e], 0.f);
;                         ((LAS float*)lds)[(4 * rt + 2 * hi + qq) * 4096 + key] = s;
;                         const bool ok = key <= t0 + 4 * rt + 2 * hi + qq;
;                         rmax[rt][qq] = fmaxf(rmax[rt][qq], ok ? s : -INFINITY); rmin[rt][qq] = fminf(rmin[rt][qq], ok ? s : INFINITY); }
.Lidx_trB:
	ds_write_b128 v222, v[228:231]
	ds_write_b128 v222, v[232:235] offset:1024
	s_nop 7
	v_max_f32_e32 v0, 0, v0
	v_max_f32_e32 v1, 0, v1
	v_max_f32_e32 v2, 0, v2
	v_max_f32_e32 v3, 0, v3
	v_max_f32_e32 v4, 0, v4
	v_max_f32_e32 v5, 0, v5
	v_max_f32_e32 v6, 0, v6
	v_max_f32_e32 v7, 0, v7
	v_pk_mul_f32 v[0:1], v[126:127], v[0:1] op_sel:[1,0] op_sel_hi:[0,1]
	v_pk_fma_f32 v[0:1], v[128:129], v[2:3], v[0:1] op_sel:[1,0,0] op_sel_hi:[0,1,1]
	v_pk_fma_f32 v[0:1], v[130:131], v[4:5], v[0:1] op_sel:[1,0,0] op_sel_hi:[0,1,1]
	v_pk_fma_f32 v[0:1], v[132:133], v[6:7], v[0:1] op_sel:[1,0,0] op_sel_hi:[0,1,1]
	v_add_f32_e32 v0, v1, v0
	v_max_f32_e32 v8, 0, v8
	v_max_f32_e32 v9, 0, v9
	v_max_f32_e32 v10, 0, v10
	v_max_f32_e32 v11, 0, v11
	v_max_f32_e32 v12, 0, v12
	v_max_f32_e32 v13, 0, v13
	v_max_f32_e32 v14, 0, v14
	v_max_f32_e32 v15, 0, v15
	s_waitcnt lgkmcnt(0)
	ds_read_b128 v[244:247], v223
	ds_read_b128 v[104:107], v224
	v_pk_mul_f32 v[8:9], v[134:135], v[8:9] op_sel:[1,0] op_sel_hi:[0,1]
	v_pk_fma_f32 v[8:9], v[136:137], v[10:11], v[8:9] op_sel:[1,0,0] op_sel_hi:[0,1,1]
	v_pk_fma_f32 v[8:9], v[138:139], v[12:13], v[8:9] op_sel:[1,0,0] op_sel_hi:[0,1,1]
	v_pk_fma_f32 v[8:9], v[140:141], v[14:15], v[8:9] op_sel:[1,0,0] op_sel_hi:[0,1,1]
	v_add_f32_e32 v8, v9, v8
	v_max_f32_e32 v189, v189, v0
	v_min_f32_e32 v188, v188, v0
	ds_write2st64_b32 v196, v0, v8 offset1:64
	v_max_f32_e32 v16, 0, v16
	v_max_f32_e32 v17, 0, v17
	v_max_f32_e32 v18, 0, v18
	v_max_f32_e32 v19, 0, v19
	v_max_f32_e32 v20, 0, v20
	v_max_f32_e32 v21, 0, v21
	v_max_f32_e32 v22, 0, v22
	v_max_f32_e32 v23, 0, v23
	v_max_f32_e32 v187, v187, v8
	v_min_f32_e32 v186, v186, v8
	s_waitcnt lgkmcnt(0)
	ds_write_b128 v222, v[236:239]
	ds_write_b128 v222, v[240:243] offset:1024
	v_pk_mul_f32 v[16:17], v[142:143], v[16:17] op_sel:[1,0] op_sel_hi:[0,1]
	v_pk_fma_f32 v[16:17], v[144:145], v[18:19], v[16:17] op_sel:[1,0,0] op_sel_hi:[0,1,1]
	v_pk_fma_f32 v[16:17], v[146:147], v[20:21], v[16:17] op_sel:[1,0,0] op_sel_hi:[0,1,1]
	v_pk_fma_f32 v[16:17], v[148:149], v[22:23], v[16:17] op_sel:[1,0,0] op_sel_hi:[0,1,1]
	v_add_f32_e32 v16, v17, v16
	v_max_f32_e32 v24, 0, v24
	v_max_f32_e32 v25, 0, v25
	v_max_f32_e32 v26, 0, v26
	v_max_f32_e32 v27, 0, v27
	v_max_f32_e32 v28, 0, v28
	v_max_f32_e32 v29, 0, v29
	v_max_f32_e32 v30, 0, v30
	v_max_f32_e32 v31, 0, v31
	v_add_u32_e32 v3, 0x10000, v196
	s_waitcnt lgkmcnt(0)
	ds_read_b128 v[100:103], v223
	ds_read_b128 v[96:99], v224
	v_pk_mul_f32 v[24:25], v[150:151], v[24:25] op_sel:[1,0] op_sel_hi:[0,1]
	v_pk_fma_f32 v[24:25], v[152:153], v[26:27], v[24:25] op_sel:[1,0,0] op_sel_hi:[0,1,1]
	v_pk_fma_f32 v[24:25], v[154:155], v[28:29], v[24:25] op_sel:[1,0,0] op_sel_hi:[0,1,1]
	v_pk_fma_f32 v[24:25], v[156:157], v[30:31], v[24:25] op_sel:[1,0,0] op_sel_hi:[0,1,1]
	v_add_f32_e32 v24, v25, v24
	ds_write_b32 v3, v16
	v_max_f32_e32 v185, v185, v16
	v_min_f32_e32 v184, v184, v16
	v_add_u32_e32 v3, 0x14000, v196
	v_add_u32_e32 v196, 0x400, v196
	s_nop 0
	ds_write_b32 v3, v24
	v_max_f32_e32 v183, v183, v24
	v_min_f32_e32 v123, v123, v24
	s_mov_b32 s6, s3
	s_branch .Lidx_loopA
.Lidx_last:
	s_waitcnt lgkmcnt(0)
	v_mfma_f32_32x32x16_bf16 v[0:15], v[72:75], v[244:247], 0
	v_add_u32_e32 v197, s6, v110
	v_mfma_f32_32x32x16_bf16 v[16:31], v[88:91], v[244:247], 0
	v_mfma_f32_32x32x16_bf16 v[0:15], v[64:67], v[104:107], v[0:15]
	v_mfma_f32_32x32x16_bf16 v[16:31], v[80:83], v[104:107], v[16:31]
	v_mfma_f32_32x32x16_bf16 v[0:15], v[68:71], v[100:103], v[0:15]
	v_mfma_f32_32x32x16_bf16 v[16:31], v[84:87], v[100:103], v[16:31]
	v_mfma_f32_32x32x16_bf16 v[0:15], v[76:79], v[96:99], v[0:15]
	v_mfma_f32_32x32x16_bf16 v[16:31], v[92:95], v[96:99], v[16:31]
	s_nop 7
	v_max_f32_e32 v0, 0, v0
	v_max_f32_e32 v1, 0, v1
	v_max_f32_e32 v2, 0, v2
	v_max_f32_e32 v3, 0, v3
	v_max_f32_e32 v4, 0, v4
	v_max_f32_e32 v5, 0, v5
	v_max_f32_e32 v6, 0, v6
	v_max_f32_e32 v7, 0, v7
	v_pk_mul_f32 v[0:1], v[126:127], v[0:1] op_sel:[1,0] op_sel_hi:[0,1]
	v_pk_fma_f32 v[0:1], v[128:129], v[2:3], v[0:1] op_sel:[1,0,0] op_sel_hi:[0,1,1]
	v_pk_fma_f32 v[0:1], v[130:131], v[4:5], v[0:1] op_sel:[1,0,0] op_sel_hi:[0,1,1]
	v_pk_fma_f32 v[0:1], v[132:133], v[6:7], v[0:1] op_sel:[1,0,0] op_sel_hi:[0,1,1]
	v_add_f32_e32 v0, v1, v0
	v_max_f32_e32 v8, 0, v8
	v_max_f32_e32 v9, 0, v9
	v_max_f32_e32 v10, 0, v10
	v_max_f32_e32 v11, 0, v11
	v_max_f32_e32 v12, 0, v12
	v_max_f32_e32 v13, 0, v13
	v_max_f32_e32 v14, 0, v14
	v_max_f32_e32 v15, 0, v15
	v_pk_mul_f32 v[8:9], v[134:135], v[8:9] op_sel:[1,0] op_sel_hi:[0,1]
	v_pk_fma_f32 v[8:9], v[136:137], v[10:11], v[8:9] op_sel:[1,0,0] op_sel_hi:[0,1,1]
	v_pk_fma_f32 v[8:9], v[138:139], v[12:13], v[8:9] op_sel:[1,0,0] op_sel_hi:[0,1,1]
	v_pk_fma_f32 v[8:9], v[140:141], v[14:15], v[8:9] op_sel:[1,0,0] op_sel_hi:[0,1,1]
	v_cmp_gt_i32_e32 vcc, v197, v190
	s_nop 1
	v_cndmask_b32_e32 v1, v0, v178, vcc
	v_cndmask_b32_e32 v2, v0, v179, vcc
	v_max_f32_e32 v189, v189, v1
	v_min_f32_e32 v188, v188, v2
	v_add_f32_e32 v8, v9, v8
	v_cmp_gt_i32_e32 vcc, v197, v191
	ds_write2st64_b32 v196, v0, v8 offset1:64
	v_max_f32_e32 v16, 0, v16
	v_max_f32_e32 v17, 0, v17
	v_max_f32_e32 v18, 0, v18
	v_cndmask_b32_e32 v1, v8, v178, vcc
	v_cndmask_b32_e32 v2, v8, v179, vcc
	v_max_f32_e32 v187, v187, v1
	v_min_f32_e32 v186, v186, v2
	v_max_f32_e32 v19, 0, v19
	v_max_f32_e32 v20, 0, v20
	v_max_f32_e32 v21, 0, v21
	v_max_f32_e32 v22, 0, v22
	v_max_f32_e32 v23, 0, v23
	v_pk_mul_f32 v[16:17], v[142:143], v[16:17] op_sel:[1,0] op_sel_hi:[0,1]
	v_pk_fma_f32 v[16:17], v[144:145], v[18:19], v[16:17] op_sel:[1,0,0] op_sel_hi:[0,1,1]
	v_pk_fma_f32 v[16:17], v[146:147], v[20:21], v[16:17] op_sel:[1,0,0] op_sel_hi:[0,1,1]
	v_pk_fma_f32 v[16:17], v[148:149], v[22:23], v[16:17] op_sel:[1,0,0] op_sel_hi:[0,1,1]
	v_add_f32_e32 v16, v17, v16
	v_max_f32_e32 v24, 0, v24
	v_max_f32_e32 v25, 0, v25
	v_max_f32_e32 v26, 0, v26
	v_max_f32_e32 v27, 0, v27
	v_max_f32_e32 v28, 0, v28
	v_max_f32_e32 v29, 0, v29
	v_max_f32_e32 v30, 0, v30
	v_max_f32_e32 v31, 0, v31
	v_pk_mul_f32 v[24:25], v[150:151], v[24:25] op_sel:[1,0] op_sel_hi:[0,1]
	v_pk_fma_f32 v[24:25], v[152:153], v[26:27], v[24:25] op_sel:[1,0,0] op_sel_hi:[0,1,1]
	v_pk_fma_f32 v[24:25], v[154:155], v[28:29], v[24:25] op_sel:[1,0,0] op_sel_hi:[0,1,1]
	v_pk_fma_f32 v[24:25], v[156:157], v[30:31], v[24:25] op_sel:[1,0,0] op_sel_hi:[0,1,1]
	v_cmp_gt_i32_e32 vcc, v197, v192
	v_add_u32_e32 v3, 0x10000, v196
	s_nop 1
	ds_write_b32 v3, v16
	v_cndmask_b32_e32 v1, v16, v178, vcc
	v_cndmask_b32_e32 v2, v16, v179, vcc
	v_max_f32_e32 v185, v185, v1
	v_min_f32_e32 v184, v184, v2
	v_add_f32_e32 v24, v25, v24
	v_cmp_gt_i32_e32 vcc, v197, v193
	v_add_u32_e32 v3, 0x14000, v196
	v_add_u32_e32 v196, 0x400, v196
	s_nop 0
	ds_write_b32 v3, v24
	v_cndmask_b32_e32 v1, v24, v178, vcc
	v_cndmask_b32_e32 v2, v24, v179, vcc
	v_max_f32_e32 v183, v183, v1
	v_min_f32_e32 v123, v123, v2
	s_branch .LBB0_874
